# MLA-up q rope epilogue: preload 16 cos/sin pairs once per sub-tile (one vmcnt wait), lane^16 partner via permlane16_swap instead of ds_bpermute
# speedup vs baseline: 1.0993x; 1.0120x over previous
; DI unsigned pk2(float lo, float hi) { f32x2 v = {lo, hi}; b16x2 r = __builtin_convertvector(v, b16x2); return __builtin_bit_cast(unsigned, r); }
; DI void phase_mla_up(const Params& p, int layer, char* lds) {
;     ...
;       auto epi = [&](const f32x16& acc, const int c0) {
;         if (part == 0) {
;           const bool is_rope = (c0 % 96 == 64);
;           u16* qp = QB + (size_t)rowb * QW + c0 + l32;
;           const f32x2* rp = rt + (size_t)srow * 16 + (l32 & 15);
; #pragma unroll
;           for (int r = 0; r < 16; ++r) {
;             const int ro = (r & 3) + 8 * (r >> 2);
;             float v = acc[r] * rv[r];
;             if (is_rope) {
;               float o = __shfl_xor(v, 16);
;               f32x2 cs = rp[ro * 16];
;               v = (l32 < 16) ? (v * cs[0] - o * cs[1]) : (v * cs[0] + o * cs[1]);
;             }
;             qp[ro * QW] = (u16)(pk2(v, 0.f) & 0xffffu);
;           }
.LBB0_228:
	s_andn2_b64 vcc, exec, s[12:13]
	s_cbranch_vccnz .LBB0_262
	v_mul_hi_i32 v4, v78, s95
	v_lshrrev_b32_e32 v79, 31, v4
	v_lshrrev_b32_e32 v4, 4, v4
	v_add_u32_e32 v4, v4, v79
	v_mul_lo_u32 v4, v4, s61
	v_sub_u32_e32 v4, v78, v4
	v_cmp_eq_u32_e64 s[12:13], 64, v4
	s_and_b64 vcc, exec, s[12:13]
	s_cbranch_vccz .Lrope0_skip
	global_load_dwordx2 v[116:117], v[76:77], off
	global_load_dwordx2 v[118:119], v[76:77], off offset:128
	global_load_dwordx2 v[120:121], v[76:77], off offset:256
	global_load_dwordx2 v[122:123], v[76:77], off offset:384
	global_load_dwordx2 v[124:125], v[76:77], off offset:1024
	global_load_dwordx2 v[126:127], v[76:77], off offset:1152
	global_load_dwordx2 v[128:129], v[76:77], off offset:1280
	global_load_dwordx2 v[130:131], v[76:77], off offset:1408
	global_load_dwordx2 v[132:133], v[76:77], off offset:2048
	global_load_dwordx2 v[134:135], v[76:77], off offset:2176
	global_load_dwordx2 v[136:137], v[76:77], off offset:2304
	global_load_dwordx2 v[138:139], v[76:77], off offset:2432
	global_load_dwordx2 v[140:141], v[76:77], off offset:3072
	global_load_dwordx2 v[142:143], v[76:77], off offset:3200
	global_load_dwordx2 v[144:145], v[76:77], off offset:3328
	global_load_dwordx2 v[146:147], v[76:77], off offset:3456
	s_waitcnt vmcnt(0)
.Lrope0_skip:
	v_mul_f32_e32 v4, v95, v22
	s_and_saveexec_b64 s[54:55], s[12:13]
	s_cbranch_execz .LBB0_231
	v_mov_b32_e32 v114, v4
	v_mov_b32_e32 v115, v4
	s_nop 1
	v_permlane16_swap_b32_e32 v114, v115
	v_cndmask_b32_e64 v114, v114, v115, s[8:9]
	v_mul_f32_e32 v114, v117, v114
	v_cndmask_b32_e64 v114, v114, -v114, s[8:9]
	v_fmac_f32_e32 v114, v4, v116
	v_mov_b32_e32 v4, v114
.LBB0_231:
	s_or_b64 exec, exec, s[54:55]
	v_ashrrev_i32_e32 v79, 31, v78
	v_lshl_add_u64 v[80:81], v[78:79], 1, v[74:75]
	v_cvt_pk_bf16_f32 v4, v4, s0
	global_store_short v[80:81], v4, off
	v_mul_f32_e32 v4, v96, v23
	s_and_saveexec_b64 s[54:55], s[12:13]
	s_cbranch_execz .LBB0_233
	v_mov_b32_e32 v114, v4
	v_mov_b32_e32 v115, v4
	s_nop 1
	v_permlane16_swap_b32_e32 v114, v115
	v_cndmask_b32_e64 v114, v114, v115, s[8:9]
	v_mul_f32_e32 v114, v119, v114
	v_cndmask_b32_e64 v114, v114, -v114, s[8:9]
	v_fmac_f32_e32 v114, v4, v118
	v_mov_b32_e32 v4, v114
.LBB0_233:
	s_or_b64 exec, exec, s[54:55]
	v_cvt_pk_bf16_f32 v4, v4, s0
	global_store_short v[80:81], v4, off offset:1152
	v_mul_f32_e32 v4, v97, v24
	s_and_saveexec_b64 s[54:55], s[12:13]
	s_cbranch_execz .LBB0_235
	v_mov_b32_e32 v114, v4
	v_mov_b32_e32 v115, v4
	s_nop 1
	v_permlane16_swap_b32_e32 v114, v115
	v_cndmask_b32_e64 v114, v114, v115, s[8:9]
	v_mul_f32_e32 v114, v121, v114
	v_cndmask_b32_e64 v114, v114, -v114, s[8:9]
	v_fmac_f32_e32 v114, v4, v120
	v_mov_b32_e32 v4, v114
.LBB0_235:
	s_or_b64 exec, exec, s[54:55]
	v_cvt_pk_bf16_f32 v4, v4, s0
	global_store_short v[80:81], v4, off offset:2304
	v_mul_f32_e32 v4, v98, v25
	s_and_saveexec_b64 s[54:55], s[12:13]
	s_cbranch_execz .LBB0_237
	v_mov_b32_e32 v114, v4
	v_mov_b32_e32 v115, v4
	s_nop 1
	v_permlane16_swap_b32_e32 v114, v115
	v_cndmask_b32_e64 v114, v114, v115, s[8:9]
	v_mul_f32_e32 v114, v123, v114
	v_cndmask_b32_e64 v114, v114, -v114, s[8:9]
	v_fmac_f32_e32 v114, v4, v122
	v_mov_b32_e32 v4, v114
.LBB0_237:
	s_or_b64 exec, exec, s[54:55]
	v_cvt_pk_bf16_f32 v4, v4, s0
	global_store_short v[80:81], v4, off offset:3456
	v_mul_f32_e32 v4, v99, v26
	s_and_saveexec_b64 s[54:55], s[12:13]
	s_cbranch_execz .LBB0_239
	v_mov_b32_e32 v114, v4
	v_mov_b32_e32 v115, v4
	s_nop 1
	v_permlane16_swap_b32_e32 v114, v115
	v_cndmask_b32_e64 v114, v114, v115, s[8:9]
	v_mul_f32_e32 v114, v125, v114
	v_cndmask_b32_e64 v114, v114, -v114, s[8:9]
	v_fmac_f32_e32 v114, v4, v124
	v_mov_b32_e32 v4, v114
.LBB0_239:
	s_or_b64 exec, exec, s[54:55]
	v_add_co_u32_e32 v22, vcc, 0x2000, v80
	v_cvt_pk_bf16_f32 v4, v4, s0
	s_nop 0
	v_addc_co_u32_e32 v23, vcc, 0, v81, vcc
	global_store_short v[22:23], v4, off offset:1024
	v_mul_f32_e32 v4, v100, v27
	s_and_saveexec_b64 s[54:55], s[12:13]
	s_cbranch_execz .LBB0_241
	v_mov_b32_e32 v114, v4
	v_mov_b32_e32 v115, v4
	s_nop 1
	v_permlane16_swap_b32_e32 v114, v115
	v_cndmask_b32_e64 v114, v114, v115, s[8:9]
	v_mul_f32_e32 v114, v127, v114
	v_cndmask_b32_e64 v114, v114, -v114, s[8:9]
	v_fmac_f32_e32 v114, v4, v126
	v_mov_b32_e32 v4, v114
.LBB0_241:
	s_or_b64 exec, exec, s[54:55]
	v_add_co_u32_e32 v22, vcc, 0x2000, v80
	v_cvt_pk_bf16_f32 v4, v4, s0
	s_nop 0
	v_addc_co_u32_e32 v23, vcc, 0, v81, vcc
	global_store_short v[22:23], v4, off offset:2176
	v_mul_f32_e32 v4, v101, v28
	s_and_saveexec_b64 s[54:55], s[12:13]
	s_cbranch_execz .LBB0_243
	v_mov_b32_e32 v114, v4
	v_mov_b32_e32 v115, v4
	s_nop 1
	v_permlane16_swap_b32_e32 v114, v115
	v_cndmask_b32_e64 v114, v114, v115, s[8:9]
	v_mul_f32_e32 v114, v129, v114
	v_cndmask_b32_e64 v114, v114, -v114, s[8:9]
	v_fmac_f32_e32 v114, v4, v128
	v_mov_b32_e32 v4, v114
; DI unsigned pk2(float lo, float hi) { f32x2 v = {lo, hi}; b16x2 r = __builtin_convertvector(v, b16x2); return __builtin_bit_cast(unsigned, r); }
; DI void phase_mla_up(const Params& p, int layer, char* lds) {
;     ...
;           for (int r = 0; r < 16; ++r) {
;             const int ro = (r & 3) + 8 * (r >> 2);
;             float v = acc[r] * rv[r];
;             if (is_rope) {
;               float o = __shfl_xor(v, 16);
;               f32x2 cs = rp[ro * 16];
;               v = (l32 < 16) ? (v * cs[0] - o * cs[1]) : (v * cs[0] + o * cs[1]);
;             }
;             qp[ro * QW] = (u16)(pk2(v, 0.f) & 0xffffu);
;           }
.LBB0_243:
	s_or_b64 exec, exec, s[54:55]
	v_add_co_u32_e32 v22, vcc, 0x2000, v80
	v_cvt_pk_bf16_f32 v4, v4, s0
	s_nop 0
	v_addc_co_u32_e32 v23, vcc, 0, v81, vcc
	global_store_short v[22:23], v4, off offset:3328
	v_mul_f32_e32 v4, v102, v29
	s_and_saveexec_b64 s[54:55], s[12:13]
	s_cbranch_execz .LBB0_245
	v_mov_b32_e32 v114, v4
	v_mov_b32_e32 v115, v4
	s_nop 1
	v_permlane16_swap_b32_e32 v114, v115
	v_cndmask_b32_e64 v114, v114, v115, s[8:9]
	v_mul_f32_e32 v114, v131, v114
	v_cndmask_b32_e64 v114, v114, -v114, s[8:9]
	v_fmac_f32_e32 v114, v4, v130
	v_mov_b32_e32 v4, v114
.LBB0_245:
	s_or_b64 exec, exec, s[54:55]
	v_add_co_u32_e32 v22, vcc, 0x3000, v80
	v_cvt_pk_bf16_f32 v4, v4, s0
	s_nop 0
	v_addc_co_u32_e32 v23, vcc, 0, v81, vcc
	global_store_short v[22:23], v4, off offset:384
	v_mul_f32_e32 v4, v103, v30
	s_and_saveexec_b64 s[54:55], s[12:13]
	s_cbranch_execz .LBB0_247
	v_mov_b32_e32 v114, v4
	v_mov_b32_e32 v115, v4
	s_nop 1
	v_permlane16_swap_b32_e32 v114, v115
	v_cndmask_b32_e64 v114, v114, v115, s[8:9]
	v_mul_f32_e32 v114, v133, v114
	v_cndmask_b32_e64 v114, v114, -v114, s[8:9]
	v_fmac_f32_e32 v114, v4, v132
	v_mov_b32_e32 v4, v114
.LBB0_247:
	s_or_b64 exec, exec, s[54:55]
	v_add_co_u32_e32 v22, vcc, 0x4000, v80
	v_cvt_pk_bf16_f32 v4, v4, s0
	s_nop 0
	v_addc_co_u32_e32 v23, vcc, 0, v81, vcc
	global_store_short v[22:23], v4, off offset:2048
	v_mul_f32_e32 v4, v104, v31
	s_and_saveexec_b64 s[54:55], s[12:13]
	s_cbranch_execz .LBB0_249
	v_mov_b32_e32 v114, v4
	v_mov_b32_e32 v115, v4
	s_nop 1
	v_permlane16_swap_b32_e32 v114, v115
	v_cndmask_b32_e64 v114, v114, v115, s[8:9]
	v_mul_f32_e32 v114, v135, v114
	v_cndmask_b32_e64 v114, v114, -v114, s[8:9]
	v_fmac_f32_e32 v114, v4, v134
	v_mov_b32_e32 v4, v114
.LBB0_249:
	s_or_b64 exec, exec, s[54:55]
	v_add_co_u32_e32 v22, vcc, 0x4000, v80
	v_cvt_pk_bf16_f32 v4, v4, s0
	s_nop 0
	v_addc_co_u32_e32 v23, vcc, 0, v81, vcc
	global_store_short v[22:23], v4, off offset:3200
	v_mul_f32_e32 v4, v105, v32
	s_and_saveexec_b64 s[54:55], s[12:13]
	s_cbranch_execz .LBB0_251
	v_mov_b32_e32 v114, v4
	v_mov_b32_e32 v115, v4
	s_nop 1
	v_permlane16_swap_b32_e32 v114, v115
	v_cndmask_b32_e64 v114, v114, v115, s[8:9]
	v_mul_f32_e32 v114, v137, v114
	v_cndmask_b32_e64 v114, v114, -v114, s[8:9]
	v_fmac_f32_e32 v114, v4, v136
	v_mov_b32_e32 v4, v114
.LBB0_251:
	s_or_b64 exec, exec, s[54:55]
	v_add_co_u32_e32 v22, vcc, 0x5000, v80
	v_cvt_pk_bf16_f32 v4, v4, s0
	s_nop 0
	v_addc_co_u32_e32 v23, vcc, 0, v81, vcc
	global_store_short v[22:23], v4, off offset:256
	v_mul_f32_e32 v4, v106, v33
	s_and_saveexec_b64 s[54:55], s[12:13]
	s_cbranch_execz .LBB0_253
	v_mov_b32_e32 v114, v4
	v_mov_b32_e32 v115, v4
	s_nop 1
	v_permlane16_swap_b32_e32 v114, v115
	v_cndmask_b32_e64 v114, v114, v115, s[8:9]
	v_mul_f32_e32 v114, v139, v114
	v_cndmask_b32_e64 v114, v114, -v114, s[8:9]
	v_fmac_f32_e32 v114, v4, v138
	v_mov_b32_e32 v4, v114
.LBB0_253:
	s_or_b64 exec, exec, s[54:55]
	v_add_co_u32_e32 v22, vcc, 0x5000, v80
	v_cvt_pk_bf16_f32 v4, v4, s0
	s_nop 0
	v_addc_co_u32_e32 v23, vcc, 0, v81, vcc
	global_store_short v[22:23], v4, off offset:1408
	v_mul_f32_e32 v4, v107, v34
	s_and_saveexec_b64 s[54:55], s[12:13]
	s_cbranch_execz .LBB0_255
	v_mov_b32_e32 v114, v4
	v_mov_b32_e32 v115, v4
	s_nop 1
	v_permlane16_swap_b32_e32 v114, v115
	v_cndmask_b32_e64 v114, v114, v115, s[8:9]
	v_mul_f32_e32 v114, v141, v114
	v_cndmask_b32_e64 v114, v114, -v114, s[8:9]
	v_fmac_f32_e32 v114, v4, v140
	v_mov_b32_e32 v4, v114
.LBB0_255:
	s_or_b64 exec, exec, s[54:55]
	v_add_co_u32_e32 v22, vcc, 0x6000, v80
	v_cvt_pk_bf16_f32 v4, v4, s0
	s_nop 0
	v_addc_co_u32_e32 v23, vcc, 0, v81, vcc
	global_store_short v[22:23], v4, off offset:3072
	v_mul_f32_e32 v4, v108, v35
	s_and_saveexec_b64 s[54:55], s[12:13]
	s_cbranch_execz .LBB0_257
	v_mov_b32_e32 v114, v4
	v_mov_b32_e32 v115, v4
	s_nop 1
	v_permlane16_swap_b32_e32 v114, v115
	v_cndmask_b32_e64 v114, v114, v115, s[8:9]
	v_mul_f32_e32 v114, v143, v114
	v_cndmask_b32_e64 v114, v114, -v114, s[8:9]
	v_fmac_f32_e32 v114, v4, v142
	v_mov_b32_e32 v4, v114
.LBB0_257:
	s_or_b64 exec, exec, s[54:55]
	v_add_co_u32_e32 v22, vcc, 0x7000, v80
	v_cvt_pk_bf16_f32 v4, v4, s0
	s_nop 0
	v_addc_co_u32_e32 v23, vcc, 0, v81, vcc
	global_store_short v[22:23], v4, off offset:128
	v_mul_f32_e32 v4, v109, v36
	s_and_saveexec_b64 s[54:55], s[12:13]
	s_cbranch_execz .LBB0_259
	v_mov_b32_e32 v114, v4
	v_mov_b32_e32 v115, v4
	s_nop 1
	v_permlane16_swap_b32_e32 v114, v115
	v_cndmask_b32_e64 v114, v114, v115, s[8:9]
	v_mul_f32_e32 v114, v145, v114
	v_cndmask_b32_e64 v114, v114, -v114, s[8:9]
	v_fmac_f32_e32 v114, v4, v144
	v_mov_b32_e32 v4, v114
.LBB0_259:
	s_or_b64 exec, exec, s[54:55]
	v_add_co_u32_e32 v22, vcc, 0x7000, v80
	v_cvt_pk_bf16_f32 v4, v4, s0
	s_nop 0
	v_addc_co_u32_e32 v23, vcc, 0, v81, vcc
	global_store_short v[22:23], v4, off offset:1280
	v_mul_f32_e32 v4, v110, v37
	s_and_saveexec_b64 s[54:55], s[12:13]
	s_cbranch_execz .LBB0_261
	v_mov_b32_e32 v114, v4
	v_mov_b32_e32 v115, v4
	s_nop 1
	v_permlane16_swap_b32_e32 v114, v115
	v_cndmask_b32_e64 v114, v114, v115, s[8:9]
	v_mul_f32_e32 v114, v147, v114
	v_cndmask_b32_e64 v114, v114, -v114, s[8:9]
	v_fmac_f32_e32 v114, v4, v146
	v_mov_b32_e32 v4, v114

; DI unsigned pk2(float lo, float hi) { f32x2 v = {lo, hi}; b16x2 r = __builtin_convertvector(v, b16x2); return __builtin_bit_cast(unsigned, r); }
; DI void phase_mla_up(const Params& p, int layer, char* lds) {
;     ...
;       auto epi = [&](const f32x16& acc, const int c0) {
;         if (part == 0) {
;           const bool is_rope = (c0 % 96 == 64);
;           u16* qp = QB + (size_t)rowb * QW + c0 + l32;
;           const f32x2* rp = rt + (size_t)srow * 16 + (l32 & 15);
; #pragma unroll
;           for (int r = 0; r < 16; ++r) {
;             const int ro = (r & 3) + 8 * (r >> 2);
;             float v = acc[r] * rv[r];
;             if (is_rope) {
;               float o = __shfl_xor(v, 16);
;               f32x2 cs = rp[ro * 16];
;               v = (l32 < 16) ? (v * cs[0] - o * cs[1]) : (v * cs[0] + o * cs[1]);
;             }
;             qp[ro * QW] = (u16)(pk2(v, 0.f) & 0xffffu);
;           }
.LBB0_269:
	s_andn2_b64 vcc, exec, s[12:13]
	s_cbranch_vccnz .LBB0_190
	v_mul_hi_i32 v4, v26, s95
	v_lshrrev_b32_e32 v22, 31, v4
	v_lshrrev_b32_e32 v4, 4, v4
	v_add_u32_e32 v4, v4, v22
	v_mul_lo_u32 v4, v4, s61
	v_sub_u32_e32 v4, v26, v4
	v_cmp_eq_u32_e64 s[12:13], 64, v4
	s_and_b64 vcc, exec, s[12:13]
	s_cbranch_vccz .Lrope1_skip
	global_load_dwordx2 v[116:117], v[76:77], off
	global_load_dwordx2 v[118:119], v[76:77], off offset:128
	global_load_dwordx2 v[120:121], v[76:77], off offset:256
	global_load_dwordx2 v[122:123], v[76:77], off offset:384
	global_load_dwordx2 v[124:125], v[76:77], off offset:1024
	global_load_dwordx2 v[126:127], v[76:77], off offset:1152
	global_load_dwordx2 v[128:129], v[76:77], off offset:1280
	global_load_dwordx2 v[130:131], v[76:77], off offset:1408
	global_load_dwordx2 v[132:133], v[76:77], off offset:2048
	global_load_dwordx2 v[134:135], v[76:77], off offset:2176
	global_load_dwordx2 v[136:137], v[76:77], off offset:2304
	global_load_dwordx2 v[138:139], v[76:77], off offset:2432
	global_load_dwordx2 v[140:141], v[76:77], off offset:3072
	global_load_dwordx2 v[142:143], v[76:77], off offset:3200
	global_load_dwordx2 v[144:145], v[76:77], off offset:3328
	global_load_dwordx2 v[146:147], v[76:77], off offset:3456
	s_waitcnt vmcnt(0)
.Lrope1_skip:
	v_mul_f32_e32 v4, v95, v6
	s_and_saveexec_b64 s[54:55], s[12:13]
	s_cbranch_execz .LBB0_272
	v_mov_b32_e32 v114, v4
	v_mov_b32_e32 v115, v4
	s_nop 1
	v_permlane16_swap_b32_e32 v114, v115
	v_cndmask_b32_e64 v114, v114, v115, s[8:9]
	v_mul_f32_e32 v114, v117, v114
	v_cndmask_b32_e64 v114, v114, -v114, s[8:9]
	v_fmac_f32_e32 v114, v4, v116
	v_mov_b32_e32 v4, v114
.LBB0_272:
	s_or_b64 exec, exec, s[54:55]
	v_ashrrev_i32_e32 v79, 31, v78
	v_lshl_add_u64 v[22:23], v[78:79], 1, v[74:75]
	v_cvt_pk_bf16_f32 v4, v4, s0
	global_store_short v[22:23], v4, off offset:64
	v_mul_f32_e32 v4, v96, v7
	s_and_saveexec_b64 s[54:55], s[12:13]
	s_cbranch_execz .LBB0_274
	v_mov_b32_e32 v114, v4
	v_mov_b32_e32 v115, v4
	s_nop 1
	v_permlane16_swap_b32_e32 v114, v115
	v_cndmask_b32_e64 v114, v114, v115, s[8:9]
	v_mul_f32_e32 v114, v119, v114
	v_cndmask_b32_e64 v114, v114, -v114, s[8:9]
	v_fmac_f32_e32 v114, v4, v118
	v_mov_b32_e32 v4, v114
.LBB0_274:
	s_or_b64 exec, exec, s[54:55]
	v_cvt_pk_bf16_f32 v4, v4, s0
	global_store_short v[22:23], v4, off offset:1216
	v_mul_f32_e32 v4, v97, v8
	s_and_saveexec_b64 s[54:55], s[12:13]
	s_cbranch_execz .LBB0_276
	v_mov_b32_e32 v114, v4
	v_mov_b32_e32 v115, v4
	s_nop 1
	v_permlane16_swap_b32_e32 v114, v115
	v_cndmask_b32_e64 v114, v114, v115, s[8:9]
	v_mul_f32_e32 v114, v121, v114
	v_cndmask_b32_e64 v114, v114, -v114, s[8:9]
	v_fmac_f32_e32 v114, v4, v120
	v_mov_b32_e32 v4, v114
.LBB0_276:
	s_or_b64 exec, exec, s[54:55]
	v_cvt_pk_bf16_f32 v4, v4, s0
	global_store_short v[22:23], v4, off offset:2368
	v_mul_f32_e32 v4, v98, v9
	s_and_saveexec_b64 s[54:55], s[12:13]
	s_cbranch_execz .LBB0_278
	v_mov_b32_e32 v114, v4
	v_mov_b32_e32 v115, v4
	s_nop 1
	v_permlane16_swap_b32_e32 v114, v115
	v_cndmask_b32_e64 v114, v114, v115, s[8:9]
	v_mul_f32_e32 v114, v123, v114
	v_cndmask_b32_e64 v114, v114, -v114, s[8:9]
	v_fmac_f32_e32 v114, v4, v122
	v_mov_b32_e32 v4, v114
.LBB0_278:
	s_or_b64 exec, exec, s[54:55]
	v_cvt_pk_bf16_f32 v4, v4, s0
	global_store_short v[22:23], v4, off offset:3520
	v_mul_f32_e32 v4, v99, v10
	s_and_saveexec_b64 s[54:55], s[12:13]
	s_cbranch_execz .LBB0_280
	v_mov_b32_e32 v114, v4
	v_mov_b32_e32 v115, v4
	s_nop 1
	v_permlane16_swap_b32_e32 v114, v115
	v_cndmask_b32_e64 v114, v114, v115, s[8:9]
	v_mul_f32_e32 v114, v125, v114
	v_cndmask_b32_e64 v114, v114, -v114, s[8:9]
	v_fmac_f32_e32 v114, v4, v124
	v_mov_b32_e32 v4, v114
.LBB0_280:
	s_or_b64 exec, exec, s[54:55]
	v_lshl_add_u64 v[6:7], v[22:23], 0, 64
	v_add_co_u32_e32 v8, vcc, 0x2000, v6
	v_cvt_pk_bf16_f32 v4, v4, s0
	s_nop 0
	v_addc_co_u32_e32 v9, vcc, 0, v7, vcc
	global_store_short v[8:9], v4, off offset:1024
	v_mul_f32_e32 v4, v100, v11
	s_and_saveexec_b64 s[54:55], s[12:13]
	s_cbranch_execz .LBB0_282
	v_mov_b32_e32 v114, v4
	v_mov_b32_e32 v115, v4
	s_nop 1
	v_permlane16_swap_b32_e32 v114, v115
	v_cndmask_b32_e64 v114, v114, v115, s[8:9]
	v_mul_f32_e32 v114, v127, v114
	v_cndmask_b32_e64 v114, v114, -v114, s[8:9]
	v_fmac_f32_e32 v114, v4, v126
	v_mov_b32_e32 v4, v114
.LBB0_282:
	s_or_b64 exec, exec, s[54:55]
	v_add_co_u32_e32 v8, vcc, 0x2000, v6
	v_cvt_pk_bf16_f32 v4, v4, s0
	s_nop 0
	v_addc_co_u32_e32 v9, vcc, 0, v7, vcc
	global_store_short v[8:9], v4, off offset:2176
	v_mul_f32_e32 v4, v101, v12
	s_and_saveexec_b64 s[54:55], s[12:13]
	s_cbranch_execz .LBB0_284
	v_mov_b32_e32 v114, v4
	v_mov_b32_e32 v115, v4
	s_nop 1
	v_permlane16_swap_b32_e32 v114, v115
	v_cndmask_b32_e64 v114, v114, v115, s[8:9]
	v_mul_f32_e32 v114, v129, v114
	v_cndmask_b32_e64 v114, v114, -v114, s[8:9]
	v_fmac_f32_e32 v114, v4, v128
	v_mov_b32_e32 v4, v114
; DI unsigned pk2(float lo, float hi) { f32x2 v = {lo, hi}; b16x2 r = __builtin_convertvector(v, b16x2); return __builtin_bit_cast(unsigned, r); }
; DI void phase_mla_up(const Params& p, int layer, char* lds) {
;     ...
;           for (int r = 0; r < 16; ++r) {
;             const int ro = (r & 3) + 8 * (r >> 2);
;             float v = acc[r] * rv[r];
;             if (is_rope) {
;               float o = __shfl_xor(v, 16);
;               f32x2 cs = rp[ro * 16];
;               v = (l32 < 16) ? (v * cs[0] - o * cs[1]) : (v * cs[0] + o * cs[1]);
;             }
;             qp[ro * QW] = (u16)(pk2(v, 0.f) & 0xffffu);
;           }
.LBB0_284:
	s_or_b64 exec, exec, s[54:55]
	v_add_co_u32_e32 v8, vcc, 0x2000, v6
	v_cvt_pk_bf16_f32 v4, v4, s0
	s_nop 0
	v_addc_co_u32_e32 v9, vcc, 0, v7, vcc
	global_store_short v[8:9], v4, off offset:3328
	v_mul_f32_e32 v4, v102, v13
	s_and_saveexec_b64 s[54:55], s[12:13]
	s_cbranch_execz .LBB0_286
	v_mov_b32_e32 v114, v4
	v_mov_b32_e32 v115, v4
	s_nop 1
	v_permlane16_swap_b32_e32 v114, v115
	v_cndmask_b32_e64 v114, v114, v115, s[8:9]
	v_mul_f32_e32 v114, v131, v114
	v_cndmask_b32_e64 v114, v114, -v114, s[8:9]
	v_fmac_f32_e32 v114, v4, v130
	v_mov_b32_e32 v4, v114
.LBB0_286:
	s_or_b64 exec, exec, s[54:55]
	v_add_co_u32_e32 v8, vcc, 0x3000, v6
	v_cvt_pk_bf16_f32 v4, v4, s0
	s_nop 0
	v_addc_co_u32_e32 v9, vcc, 0, v7, vcc
	global_store_short v[8:9], v4, off offset:384
	v_mul_f32_e32 v4, v103, v14
	s_and_saveexec_b64 s[54:55], s[12:13]
	s_cbranch_execz .LBB0_288
	v_mov_b32_e32 v114, v4
	v_mov_b32_e32 v115, v4
	s_nop 1
	v_permlane16_swap_b32_e32 v114, v115
	v_cndmask_b32_e64 v114, v114, v115, s[8:9]
	v_mul_f32_e32 v114, v133, v114
	v_cndmask_b32_e64 v114, v114, -v114, s[8:9]
	v_fmac_f32_e32 v114, v4, v132
	v_mov_b32_e32 v4, v114
.LBB0_288:
	s_or_b64 exec, exec, s[54:55]
	v_add_co_u32_e32 v8, vcc, 0x4000, v6
	v_cvt_pk_bf16_f32 v4, v4, s0
	s_nop 0
	v_addc_co_u32_e32 v9, vcc, 0, v7, vcc
	global_store_short v[8:9], v4, off offset:2048
	v_mul_f32_e32 v4, v104, v15
	s_and_saveexec_b64 s[54:55], s[12:13]
	s_cbranch_execz .LBB0_290
	v_mov_b32_e32 v114, v4
	v_mov_b32_e32 v115, v4
	s_nop 1
	v_permlane16_swap_b32_e32 v114, v115
	v_cndmask_b32_e64 v114, v114, v115, s[8:9]
	v_mul_f32_e32 v114, v135, v114
	v_cndmask_b32_e64 v114, v114, -v114, s[8:9]
	v_fmac_f32_e32 v114, v4, v134
	v_mov_b32_e32 v4, v114
.LBB0_290:
	s_or_b64 exec, exec, s[54:55]
	v_add_co_u32_e32 v8, vcc, 0x4000, v6
	v_cvt_pk_bf16_f32 v4, v4, s0
	s_nop 0
	v_addc_co_u32_e32 v9, vcc, 0, v7, vcc
	global_store_short v[8:9], v4, off offset:3200
	v_mul_f32_e32 v4, v105, v16
	s_and_saveexec_b64 s[54:55], s[12:13]
	s_cbranch_execz .LBB0_292
	v_mov_b32_e32 v114, v4
	v_mov_b32_e32 v115, v4
	s_nop 1
	v_permlane16_swap_b32_e32 v114, v115
	v_cndmask_b32_e64 v114, v114, v115, s[8:9]
	v_mul_f32_e32 v114, v137, v114
	v_cndmask_b32_e64 v114, v114, -v114, s[8:9]
	v_fmac_f32_e32 v114, v4, v136
	v_mov_b32_e32 v4, v114
.LBB0_292:
	s_or_b64 exec, exec, s[54:55]
	v_add_co_u32_e32 v8, vcc, 0x5000, v6
	v_cvt_pk_bf16_f32 v4, v4, s0
	s_nop 0
	v_addc_co_u32_e32 v9, vcc, 0, v7, vcc
	global_store_short v[8:9], v4, off offset:256
	v_mul_f32_e32 v4, v106, v17
	s_and_saveexec_b64 s[54:55], s[12:13]
	s_cbranch_execz .LBB0_294
	v_mov_b32_e32 v114, v4
	v_mov_b32_e32 v115, v4
	s_nop 1
	v_permlane16_swap_b32_e32 v114, v115
	v_cndmask_b32_e64 v114, v114, v115, s[8:9]
	v_mul_f32_e32 v114, v139, v114
	v_cndmask_b32_e64 v114, v114, -v114, s[8:9]
	v_fmac_f32_e32 v114, v4, v138
	v_mov_b32_e32 v4, v114
.LBB0_294:
	s_or_b64 exec, exec, s[54:55]
	v_add_co_u32_e32 v8, vcc, 0x5000, v6
	v_cvt_pk_bf16_f32 v4, v4, s0
	s_nop 0
	v_addc_co_u32_e32 v9, vcc, 0, v7, vcc
	global_store_short v[8:9], v4, off offset:1408
	v_mul_f32_e32 v4, v107, v18
	s_and_saveexec_b64 s[54:55], s[12:13]
	s_cbranch_execz .LBB0_296
	v_mov_b32_e32 v114, v4
	v_mov_b32_e32 v115, v4
	s_nop 1
	v_permlane16_swap_b32_e32 v114, v115
	v_cndmask_b32_e64 v114, v114, v115, s[8:9]
	v_mul_f32_e32 v114, v141, v114
	v_cndmask_b32_e64 v114, v114, -v114, s[8:9]
	v_fmac_f32_e32 v114, v4, v140
	v_mov_b32_e32 v4, v114
.LBB0_296:
	s_or_b64 exec, exec, s[54:55]
	v_add_co_u32_e32 v8, vcc, 0x6000, v6
	v_cvt_pk_bf16_f32 v4, v4, s0
	s_nop 0
	v_addc_co_u32_e32 v9, vcc, 0, v7, vcc
	global_store_short v[8:9], v4, off offset:3072
	v_mul_f32_e32 v4, v108, v19
	s_and_saveexec_b64 s[54:55], s[12:13]
	s_cbranch_execz .LBB0_298
	v_mov_b32_e32 v114, v4
	v_mov_b32_e32 v115, v4
	s_nop 1
	v_permlane16_swap_b32_e32 v114, v115
	v_cndmask_b32_e64 v114, v114, v115, s[8:9]
	v_mul_f32_e32 v114, v143, v114
	v_cndmask_b32_e64 v114, v114, -v114, s[8:9]
	v_fmac_f32_e32 v114, v4, v142
	v_mov_b32_e32 v4, v114
.LBB0_298:
	s_or_b64 exec, exec, s[54:55]
	v_add_co_u32_e32 v8, vcc, 0x7000, v6
	v_cvt_pk_bf16_f32 v4, v4, s0
	s_nop 0
	v_addc_co_u32_e32 v9, vcc, 0, v7, vcc
	global_store_short v[8:9], v4, off offset:128
	v_mul_f32_e32 v4, v109, v20
	s_and_saveexec_b64 s[54:55], s[12:13]
	s_cbranch_execz .LBB0_300
	v_mov_b32_e32 v114, v4
	v_mov_b32_e32 v115, v4
	s_nop 1
	v_permlane16_swap_b32_e32 v114, v115
	v_cndmask_b32_e64 v114, v114, v115, s[8:9]
	v_mul_f32_e32 v114, v145, v114
	v_cndmask_b32_e64 v114, v114, -v114, s[8:9]
	v_fmac_f32_e32 v114, v4, v144
	v_mov_b32_e32 v4, v114
.LBB0_300:
	s_or_b64 exec, exec, s[54:55]
	v_add_co_u32_e32 v8, vcc, 0x7000, v6
	v_cvt_pk_bf16_f32 v4, v4, s0
	s_nop 0
	v_addc_co_u32_e32 v9, vcc, 0, v7, vcc
	global_store_short v[8:9], v4, off offset:1280
	v_mul_f32_e32 v4, v110, v21
	s_and_saveexec_b64 s[54:55], s[12:13]
	s_cbranch_execz .LBB0_189
	v_mov_b32_e32 v114, v4
	v_mov_b32_e32 v115, v4
	s_nop 1
	v_permlane16_swap_b32_e32 v114, v115
	v_cndmask_b32_e64 v114, v114, v115, s[8:9]
	v_mul_f32_e32 v114, v147, v114
	v_cndmask_b32_e64 v114, v114, -v114, s[8:9]
	v_fmac_f32_e32 v114, v4, v146
	v_mov_b32_e32 v4, v114
	s_branch .LBB0_189
